# input-projection epilogue: row-norm loads of all 8 row groups in a single batch (one wait)
# speedup vs baseline: 1.0152x; 1.0004x over previous
; template <int N4> __device__ __forceinline__ float sum_parts(const float* p) {
;     f32x4 a = *(const f32x4*)p;
; #pragma unroll
;     for (int i = 1; i < N4; ++i) a += *(const f32x4*)(p + 4 * i);
;     return (a[0] + a[1]) + (a[2] + a[3]);
;     __device__ __forceinline__ void operator()(const f32x4 (&acc)[2][2][4][2], const Unit& u, int wr, int wc, int fr, int fq) const {
;     ...
;         for (int ai = 0; ai < 2; ++ai)
; #pragma unroll
;             for (int m = 0; m < 4; ++m) {
;                 const int row = row0 + ai * HALF + m * 16;
;                 const float r = __builtin_amdgcn_rsqf(sum_parts<8>(ssq_h + (size_t)row * 32) * (1.0f / 2048.0f) + 1e-6f);
; #pragma unroll
;                 for (int bj = 0; bj < 2; ++bj) {
;                     float v[8];
; #pragma unroll
;                     for (int e = 0; e < 4; ++e) { v[e] = acc[ai][bj][m][0][e] * r; v[4 + e] = acc[ai][bj][m][1][e] * r; }
;                     if (tab[bj] >= 0) rope8(v, TAB + (size_t)row * NTAB + tab[bj]);
.LBB0_343:
	s_ashr_i32 s1, s1, 2
	s_andn2_b32 s1, s1, 63
	v_lshrrev_b32_e32 v198, 4, v146
	v_and_or_b32 v146, v146, 15, s1
	v_lshl_add_u32 v146, s87, 8, v146
	v_ashrrev_i32_e32 v147, 31, v146
	v_lshlrev_b32_e32 v198, 5, v198
	v_mov_b32_e32 v199, 0
	v_lshlrev_b64 v[190:191], 7, v[146:147]
	v_lshl_add_u64 v[190:191], s[22:23], 0, v[190:191]
	v_lshl_add_u64 v[190:191], v[190:191], 0, v[198:199]
	v_mov_b32_e32 v160, 0x1000
	v_mov_b32_e32 v161, 0
	v_lshl_add_u64 v[192:193], v[160:161], 0, v[190:191]
	v_lshl_add_u64 v[194:195], v[160:161], 2, v[190:191]
	v_lshl_add_u64 v[196:197], v[160:161], 0, v[194:195]
	global_load_dwordx4 v[218:221], v[190:191], off
	global_load_dwordx4 v[222:225], v[190:191], off offset:16
	global_load_dwordx4 v[226:229], v[190:191], off offset:2048
	global_load_dwordx4 v[230:233], v[190:191], off offset:2064
	global_load_dwordx4 v[234:237], v[192:193], off
	global_load_dwordx4 v[238:241], v[192:193], off offset:16
	global_load_dwordx4 v[178:181], v[192:193], off offset:2048
	global_load_dwordx4 v[182:185], v[192:193], off offset:2064
	global_load_dwordx4 v[186:189], v[194:195], off
	global_load_dwordx4 v[154:157], v[194:195], off offset:16
	global_load_dwordx4 v[160:163], v[194:195], off offset:2048
	global_load_dwordx4 v[164:167], v[194:195], off offset:2064
	global_load_dwordx4 v[242:245], v[196:197], off
	global_load_dwordx4 v[246:249], v[196:197], off offset:16
	global_load_dwordx4 v[250:253], v[196:197], off offset:2048
	global_load_dwordx4 v[206:209], v[196:197], off offset:2064
	s_waitcnt vmcnt(0)
	v_pk_add_f32 v[218:219], v[218:219], v[220:221]
	v_pk_add_f32 v[222:223], v[222:223], v[224:225]
	v_pk_add_f32 v[218:219], v[218:219], v[222:223]
	v_add_f32_e32 v168, v218, v219
	v_pk_add_f32 v[226:227], v[226:227], v[228:229]
	v_pk_add_f32 v[230:231], v[230:231], v[232:233]
	v_pk_add_f32 v[226:227], v[226:227], v[230:231]
	v_add_f32_e32 v169, v226, v227
	v_pk_add_f32 v[234:235], v[234:235], v[236:237]
	v_pk_add_f32 v[238:239], v[238:239], v[240:241]
	v_pk_add_f32 v[234:235], v[234:235], v[238:239]
	v_add_f32_e32 v170, v234, v235
	v_pk_add_f32 v[178:179], v[178:179], v[180:181]
	v_pk_add_f32 v[182:183], v[182:183], v[184:185]
	v_pk_add_f32 v[178:179], v[178:179], v[182:183]
	v_add_f32_e32 v171, v178, v179
	v_pk_add_f32 v[186:187], v[186:187], v[188:189]
	v_pk_add_f32 v[154:155], v[154:155], v[156:157]
	v_pk_add_f32 v[186:187], v[186:187], v[154:155]
	v_add_f32_e32 v172, v186, v187
	v_pk_add_f32 v[160:161], v[160:161], v[162:163]
	v_pk_add_f32 v[164:165], v[164:165], v[166:167]
	v_pk_add_f32 v[160:161], v[160:161], v[164:165]
	v_add_f32_e32 v173, v160, v161
	v_pk_add_f32 v[242:243], v[242:243], v[244:245]
	v_pk_add_f32 v[246:247], v[246:247], v[248:249]
	v_pk_add_f32 v[242:243], v[242:243], v[246:247]
	v_add_f32_e32 v174, v242, v243
	v_pk_add_f32 v[250:251], v[250:251], v[252:253]
	v_pk_add_f32 v[206:207], v[206:207], v[208:209]
	v_pk_add_f32 v[250:251], v[250:251], v[206:207]
	v_add_f32_e32 v175, v250, v251
	v_mov_b32_e32 v234, v168
	v_mov_b32_e32 v235, v169
	v_mov_b32_e32 v236, v170
	v_mov_b32_e32 v237, v171
	v_mov_b32_e32 v238, v172
	v_mov_b32_e32 v239, v173
	v_mov_b32_e32 v240, v174
	v_mov_b32_e32 v241, v175
	v_permlane32_swap_b32_e32 v168, v234
	v_permlane32_swap_b32_e32 v169, v235
	v_permlane32_swap_b32_e32 v170, v236
	v_permlane32_swap_b32_e32 v171, v237
	v_permlane32_swap_b32_e32 v172, v238
	v_permlane32_swap_b32_e32 v173, v239
	v_permlane32_swap_b32_e32 v174, v240
	v_permlane32_swap_b32_e32 v175, v241
	v_add_f32_e32 v168, v168, v234
	v_add_f32_e32 v169, v169, v235
	v_add_f32_e32 v170, v170, v236
	v_add_f32_e32 v171, v171, v237
	v_add_f32_e32 v172, v172, v238
	v_add_f32_e32 v173, v173, v239
	v_add_f32_e32 v174, v174, v240
	v_add_f32_e32 v175, v175, v241
	v_mov_b32_e32 v234, v168
	v_mov_b32_e32 v235, v169
	v_mov_b32_e32 v236, v170
	v_mov_b32_e32 v237, v171
	v_mov_b32_e32 v238, v172
	v_mov_b32_e32 v239, v173
	v_mov_b32_e32 v240, v174
	v_mov_b32_e32 v241, v175
	v_permlane16_swap_b32_e32 v168, v234
	v_permlane16_swap_b32_e32 v169, v235
	v_permlane16_swap_b32_e32 v170, v236
	v_permlane16_swap_b32_e32 v171, v237
	v_permlane16_swap_b32_e32 v172, v238
	v_permlane16_swap_b32_e32 v173, v239
	v_permlane16_swap_b32_e32 v174, v240
	v_permlane16_swap_b32_e32 v175, v241
	v_add_f32_e32 v168, v168, v234
	v_add_f32_e32 v169, v169, v235
	v_add_f32_e32 v170, v170, v236
	v_add_f32_e32 v171, v171, v237
	v_add_f32_e32 v172, v172, v238
	v_add_f32_e32 v173, v173, v239
	v_add_f32_e32 v174, v174, v240
	v_add_f32_e32 v175, v175, v241
	v_fmamk_f32 v168, v168, 0x3a000000, v204
	v_fmamk_f32 v169, v169, 0x3a000000, v204
	v_fmamk_f32 v170, v170, 0x3a000000, v204
	v_fmamk_f32 v171, v171, 0x3a000000, v204
	v_fmamk_f32 v172, v172, 0x3a000000, v204
	v_fmamk_f32 v173, v173, 0x3a000000, v204
	v_fmamk_f32 v174, v174, 0x3a000000, v204
	v_fmamk_f32 v175, v175, 0x3a000000, v204
	v_rsq_f32_e32 v168, v168
	v_rsq_f32_e32 v169, v169
	v_rsq_f32_e32 v170, v170
	v_rsq_f32_e32 v171, v171
	v_rsq_f32_e32 v172, v172
	v_rsq_f32_e32 v173, v173
	v_rsq_f32_e32 v174, v174
	v_rsq_f32_e32 v175, v175
	s_movk_i32 s1, 0x1c0
	v_mad_i64_i32 v[156:157], s[6:7], v146, s1, 0
	v_mov_b32_e32 v154, v168
	v_cmp_lt_i32_e64 s[6:7], -1, v0
	v_lshl_add_u64 v[156:157], s[70:71], 0, v[156:157]
	v_pk_mul_f32 v[2:3], v[2:3], v[154:155] op_sel_hi:[1,0]
	v_pk_mul_f32 v[6:7], v[6:7], v[154:155] op_sel_hi:[1,0]
	v_pk_mul_f32 v[4:5], v[4:5], v[154:155] op_sel_hi:[1,0]
	v_pk_mul_f32 v[8:9], v[8:9], v[154:155] op_sel_hi:[1,0]
	s_and_saveexec_b64 s[8:9], s[6:7]
	s_cbranch_execz .LBB0_345
	v_lshl_add_u64 v[160:161], v[0:1], 3, v[156:157]
	global_load_dwordx4 v[184:187], v[160:161], off offset:16
	global_load_dwordx4 v[180:183], v[160:161], off
	s_waitcnt vmcnt(0)
	v_pk_mul_f32 v[160:161], v[2:3], v[180:181] op_sel:[1,1] op_sel_hi:[1,0]
	s_nop 0
	v_pk_fma_f32 v[178:179], v[2:3], v[180:181], v[160:161] op_sel_hi:[0,1,1] neg_lo:[0,0,1] neg_hi:[0,0,1]
	v_pk_fma_f32 v[2:3], v[2:3], v[180:181], v[160:161] op_sel_hi:[0,1,1]
	v_pk_mul_f32 v[160:161], v[4:5], v[182:183] op_sel:[1,1] op_sel_hi:[1,0]
	v_mul_f32_e32 v2, v9, v187
	v_pk_fma_f32 v[180:181], v[4:5], v[182:183], v[160:161] op_sel_hi:[0,1,1] neg_lo:[0,0,1] neg_hi:[0,0,1]
	v_pk_fma_f32 v[4:5], v[4:5], v[182:183], v[160:161] op_sel_hi:[0,1,1]
	v_pk_mul_f32 v[160:161], v[6:7], v[184:185] op_sel:[1,1] op_sel_hi:[1,0]
	v_mov_b32_e32 v179, v3
	v_pk_fma_f32 v[182:183], v[6:7], v[184:185], v[160:161] op_sel_hi:[0,1,1] neg_lo:[0,0,1] neg_hi:[0,0,1]
	v_pk_fma_f32 v[6:7], v[6:7], v[184:185], v[160:161] op_sel_hi:[0,1,1]
	v_pk_fma_f32 v[184:185], v[8:9], v[186:187], v[2:3] op_sel_hi:[1,1,0] neg_lo:[0,0,1] neg_hi:[0,0,1]
	v_mul_f32_e32 v2, v9, v186
	v_pk_fma_f32 v[8:9], v[8:9], v[186:187], v[2:3] op_sel:[0,1,0] op_sel_hi:[1,0,0]
	v_mov_b32_e32 v181, v5
	v_mov_b32_e32 v183, v7
	v_mov_b32_e32 v185, v8
	v_mov_b64_e32 v[2:3], v[178:179]
	v_mov_b64_e32 v[4:5], v[180:181]
	v_mov_b64_e32 v[6:7], v[182:183]
	v_mov_b64_e32 v[8:9], v[184:185]
